# FoX attention tile body: forget-bias LDS reads issued with the K fragment reads at the start of the QK part
# baseline (speedup 1.0000x reference)
; #define MFMA(a, b, c) __builtin_amdgcn_mfma_f32_16x16x32_bf16((a), (b), (c), 0, 0, 0)
; template <int DK, bool BIAS> ...
;     ...
; #pragma unroll
;       for (int ks = 0; ks < KS; ++ks)
; #pragma unroll
;         for (int kt = 0; kt < 4; ++kt) { const bf16x8 ak = *(const bf16x8*)(Ksm + (buf * 64 + 16 * kt + fr) * KST + 32 * ks + 8 * fq);
; #pragma unroll
;           for (int qi = 0; qi < 2; ++qi) S[kt][qi] = MFMA(ak, qf[qi][ks], S[kt][qi]); }
;       bf16x8 pf[2][2];
;       if (64 * j + 63 > q0 + 32 * w) {
; #pragma unroll
;         for (int qi = 0; qi < 2; ++qi) { const int qg = q0 + 32 * w + 16 * qi + fr;
; #pragma unroll
;           for (int kt = 0; kt < 4; ++kt)
; #pragma unroll
;             for (int r = 0; r < 4; ++r) { const int kg = 64 * j + 16 * kt + 4 * fq + r; if (kg > qg) S[kt][qi][r] = -1e30f; } }
;       }
; #pragma unroll
;       for (int qi = 0; qi < 2; ++qi) {
;         float mx = -3e38f;
;         if (BIAS) {
; #pragma unroll
;           for (int kt = 0; kt < 4; ++kt) { const f32x4 nf = *(const f32x4*)(fkm + buf * 64 + 16 * kt + 4 * fq);
; #pragma unroll
;             for (int r = 0; r < 4; ++r) { const float t = fmaf(S[kt][qi][r], sc2, nf[r]); S[kt][qi][r] = t; mx = fmaxf(mx, t); } }
.LBB0_1772:
	s_and_saveexec_b64 s[0:1], s[8:9]
	s_cbranch_execz .LBB0_1778
	v_cmp_le_i32_e32 vcc, s38, v167
	s_and_saveexec_b64 s[94:95], vcc
	s_cbranch_execz .LBB0_1777
	ds_read_b128 v[80:83], v169 offset:4608
	ds_read_b128 v[64:67], v169
	ds_read_b128 v[84:87], v169 offset:64
	ds_read_b128 v[72:75], v169 offset:2304
	ds_read_b128 v[210:213], v169 offset:6912
	ds_read_b128 v[214:217], v169 offset:2368
	ds_read_b128 v[218:221], v169 offset:6976
	ds_read_b128 v[222:225], v169 offset:4672
	ds_read_b128 v[174:177], v168 offset:36864
	ds_read_b128 v[194:197], v168 offset:36928
	ds_read_b128 v[242:245], v168 offset:36992
	ds_read_b128 v[246:249], v168 offset:37056
	s_add_i32 s18, s38, 63
	v_cmp_gt_i32_e32 vcc, s18, v127
	s_waitcnt lgkmcnt(11)
	v_mfma_f32_16x16x32_bf16 v[90:93], v[80:83], v[4:7], 0
	v_mfma_f32_16x16x32_bf16 v[94:97], v[80:83], v[12:15], 0
	s_waitcnt lgkmcnt(10)
	v_mfma_f32_16x16x32_bf16 v[68:71], v[64:67], v[4:7], 0
	s_waitcnt lgkmcnt(7)
	v_mfma_f32_16x16x32_bf16 v[116:119], v[210:213], v[4:7], 0
	v_mfma_f32_16x16x32_bf16 v[120:123], v[210:213], v[12:15], 0
	v_mfma_f32_16x16x32_bf16 v[80:83], v[84:87], v[0:3], v[68:71]
	v_mfma_f32_16x16x32_bf16 v[64:67], v[64:67], v[12:15], 0
	v_mfma_f32_16x16x32_bf16 v[76:79], v[72:75], v[4:7], 0
	v_mfma_f32_16x16x32_bf16 v[72:75], v[72:75], v[12:15], 0
	v_mfma_f32_16x16x32_bf16 v[64:67], v[84:87], v[8:11], v[64:67]
	s_waitcnt lgkmcnt(6)
	v_mfma_f32_16x16x32_bf16 v[86:89], v[214:217], v[0:3], v[76:79]
	v_mfma_f32_16x16x32_bf16 v[68:71], v[214:217], v[8:11], v[72:75]
	s_waitcnt lgkmcnt(4)
	v_mfma_f32_16x16x32_bf16 v[90:93], v[222:225], v[0:3], v[90:93]
	v_mfma_f32_16x16x32_bf16 v[72:75], v[222:225], v[8:11], v[94:97]
	v_mfma_f32_16x16x32_bf16 v[94:97], v[218:221], v[0:3], v[116:119]
	v_mfma_f32_16x16x32_bf16 v[76:79], v[218:221], v[8:11], v[120:123]
	s_and_saveexec_b64 s[18:19], vcc
	s_cbranch_execz .LBB0_1776
	v_add_u32_e32 v85, s38, v103
	v_mov_b32_e32 v84, s30
	v_cmp_gt_i32_e32 vcc, v85, v158
	v_add_u32_e32 v113, 2, v85
	v_add_u32_e32 v115, 3, v85
	v_cndmask_b32_e32 v84, v80, v84, vcc
	v_cmp_lt_i32_e32 vcc, v85, v158
	v_add_u32_e32 v116, 16, v85
	v_add_u32_e32 v117, 17, v85
	v_cndmask_b32_e32 v80, v84, v80, vcc
	v_cndmask_b32_e32 v81, v193, v81, vcc
	v_cmp_le_i32_e32 vcc, v113, v158
	v_mov_b32_e32 v84, s30
	v_add_u32_e32 v118, 18, v85
	v_cndmask_b32_e32 v82, v193, v82, vcc
	v_cmp_le_i32_e32 vcc, v115, v158
	v_add_u32_e32 v119, 19, v85
	v_add_u32_e32 v120, 32, v85
	v_cndmask_b32_e32 v83, v193, v83, vcc
	v_cmp_gt_i32_e32 vcc, v116, v158
	v_add_u32_e32 v121, 33, v85
	v_add_u32_e32 v122, 34, v85
	v_cndmask_b32_e32 v86, v86, v84, vcc
	v_cmp_le_i32_e32 vcc, v117, v158
	v_add_u32_e32 v123, 35, v85
	v_add_u32_e32 v124, 48, v85
	v_cndmask_b32_e32 v87, v193, v87, vcc
	v_cmp_le_i32_e32 vcc, v118, v158
	v_add_u32_e32 v125, 49, v85
	v_add_u32_e32 v126, 50, v85
	v_cndmask_b32_e32 v88, v193, v88, vcc
	v_cmp_le_i32_e32 vcc, v119, v158
	v_add_u32_e32 v131, 51, v85
	s_nop 0
	v_cndmask_b32_e32 v89, v193, v89, vcc
	v_cmp_gt_i32_e32 vcc, v120, v158
	v_cmp_le_i32_e64 s[100:101], v121, v158
	s_nop 0
	v_cndmask_b32_e32 v90, v90, v84, vcc
	v_cndmask_b32_e64 v91, v193, v91, s[100:101]
	v_cmp_le_i32_e32 vcc, v122, v158
	v_cmp_le_i32_e64 s[100:101], v123, v158
	s_nop 0
	v_cndmask_b32_e32 v92, v193, v92, vcc
	v_cndmask_b32_e64 v93, v193, v93, s[100:101]
	v_cmp_gt_i32_e32 vcc, v124, v158
	v_cmp_le_i32_e64 s[100:101], v125, v158
	s_nop 0
	v_cndmask_b32_e32 v94, v94, v84, vcc
	v_cndmask_b32_e64 v95, v193, v95, s[100:101]
	v_cmp_le_i32_e32 vcc, v126, v158
	v_cmp_le_i32_e64 s[100:101], v131, v158
	s_nop 0
	v_cndmask_b32_e32 v96, v193, v96, vcc
	v_cndmask_b32_e64 v97, v193, v97, s[100:101]
	v_cmp_gt_i32_e32 vcc, v85, v105
	s_nop 1
	v_cndmask_b32_e32 v84, v64, v84, vcc
	v_cmp_lt_i32_e32 vcc, v85, v105
	s_nop 1
	v_cndmask_b32_e32 v64, v84, v64, vcc
	v_cndmask_b32_e32 v65, v193, v65, vcc
	v_cmp_le_i32_e32 vcc, v113, v105
	v_mov_b32_e32 v84, s30
	s_nop 0
	v_cndmask_b32_e32 v66, v193, v66, vcc
	v_cmp_le_i32_e32 vcc, v115, v105
	v_cmp_gt_i32_e64 s[100:101], v116, v105
	s_nop 0
	v_cndmask_b32_e32 v67, v193, v67, vcc
	v_cndmask_b32_e64 v68, v68, v84, s[100:101]
	v_cmp_le_i32_e32 vcc, v117, v105
	v_cmp_le_i32_e64 s[100:101], v118, v105
	s_nop 0
	v_cndmask_b32_e32 v69, v193, v69, vcc
	v_cndmask_b32_e64 v70, v193, v70, s[100:101]
	v_cmp_le_i32_e32 vcc, v119, v105
	v_cmp_gt_i32_e64 s[100:101], v120, v105
	s_nop 0
	v_cndmask_b32_e32 v71, v193, v71, vcc
	v_cndmask_b32_e64 v72, v72, v84, s[100:101]
	v_cmp_le_i32_e32 vcc, v121, v105
	v_cmp_le_i32_e64 s[100:101], v122, v105
	s_nop 0
	v_cndmask_b32_e32 v73, v193, v73, vcc
	v_cndmask_b32_e64 v74, v193, v74, s[100:101]
	v_cmp_le_i32_e32 vcc, v123, v105
	v_cmp_gt_i32_e64 s[100:101], v124, v105
	s_nop 0
	v_cndmask_b32_e32 v75, v193, v75, vcc
	v_cndmask_b32_e64 v76, v76, v84, s[100:101]
	v_cmp_le_i32_e32 vcc, v125, v105
	v_cmp_le_i32_e64 s[100:101], v126, v105
	s_nop 0
	v_cndmask_b32_e32 v77, v193, v77, vcc
	v_cndmask_b32_e64 v78, v193, v78, s[100:101]
	v_cmp_le_i32_e32 vcc, v131, v105
	s_nop 1
	v_cndmask_b32_e32 v79, v193, v79, vcc
; DEVI unsigned pk_bf16(float lo, float hi) { unsigned r; asm("v_cvt_pk_bf16_f32 %0, %1, %2" : "=v"(r) : "v"(lo), "v"(hi)); return r; }
; DEVI bf16x8 mk8(uint2 a, uint2 b) { union { uint4 u; bf16x8 v; } c; c.u = make_uint4(a.x, a.y, b.x, b.y); return c.v; }
; template <int DK, bool BIAS> ...
;     ...
; #pragma unroll
;       for (int qi = 0; qi < 2; ++qi) {
;         float mx = -3e38f;
;         if (BIAS) {
; #pragma unroll
;           for (int kt = 0; kt < 4; ++kt) { const f32x4 nf = *(const f32x4*)(fkm + buf * 64 + 16 * kt + 4 * fq);
; #pragma unroll
;             for (int r = 0; r < 4; ++r) { const float t = fmaf(S[kt][qi][r], sc2, nf[r]); S[kt][qi][r] = t; mx = fmaxf(mx, t); } }
;         } else {
; #pragma unroll
;           for (int kt = 0; kt < 4; ++kt)
; #pragma unroll
;             for (int r = 0; r < 4; ++r) mx = fmaxf(mx, S[kt][qi][r]);
;           mx *= sc2;
;         }
;         mx = fmaxf(mx, __shfl_xor(mx, 16)); mx = fmaxf(mx, __shfl_xor(mx, 32));
;         const float mold = mrun[qi], mnew = fmaxf(mold, mx);
;         mrun[qi] = mnew;
;         float ps = 0.f;
; #pragma unroll
;         for (int kt = 0; kt < 4; ++kt)
; #pragma unroll
;           for (int r = 0; r < 4; ++r) { const float pv = BIAS ? __builtin_amdgcn_exp2f(S[kt][qi][r] - mnew) : __builtin_amdgcn_exp2f(fmaf(S[kt][qi][r], sc2, -mnew)); S[kt][qi][r] = pv; ps += pv; }
;         {
;           const float alpha = __builtin_amdgcn_exp2f(mold - mnew);
;           lrun[qi] *= alpha;
; #pragma unroll
;           for (int et = 0; et < 4; ++et) O[et][qi] *= alpha;
;         }
;         lrun[qi] += ps;
; #pragma unroll
;         for (int k2 = 0; k2 < 2; ++k2) { uint2 lo, hi; lo.x = pk_bf16(S[2 * k2][qi][0], S[2 * k2][qi][1]); lo.y = pk_bf16(S[2 * k2][qi][2], S[2 * k2][qi][3]);
;           hi.x = pk_bf16(S[2 * k2 + 1][qi][0], S[2 * k2 + 1][qi][1]); hi.y = pk_bf16(S[2 * k2 + 1][qi][2], S[2 * k2 + 1][qi][3]); pf[qi][k2] = mk8(lo, hi); }
;       }
; #pragma unroll
;       for (int k2 = 0; k2 < 2; ++k2)
; #pragma unroll
;         for (int et = 0; et < 4; ++et) {
;           const uint2 v0 = *(const uint2*)(Vtm + (buf * 64 + 16 * et + fr) * 72 + 32 * k2 + 4 * fq), v1 = *(const uint2*)(Vtm + (buf * 64 + 16 * et + fr) * 72 + 32 * k2 + 16 + 4 * fq);
;           const bf16x8 va = mk8(v0, v1);
.LBB0_1776:
	s_or_b64 exec, exec, s[18:19]
	s_mov_b32 s100, 0x3e38aa3b
	s_mov_b32 s101, 0x3e38aa3b
	v_lshlrev_b32_e32 v250, 2, v186
	s_waitcnt lgkmcnt(3)
	v_pk_fma_f32 v[210:211], v[80:81], s[100:101], v[174:175]
	v_pk_fma_f32 v[212:213], v[82:83], s[100:101], v[176:177]
	v_pk_fma_f32 v[226:227], v[64:65], s[100:101], v[174:175]
	v_pk_fma_f32 v[228:229], v[66:67], s[100:101], v[176:177]
	s_waitcnt lgkmcnt(2)
	v_pk_fma_f32 v[214:215], v[86:87], s[100:101], v[194:195]
	v_pk_fma_f32 v[216:217], v[88:89], s[100:101], v[196:197]
	v_pk_fma_f32 v[230:231], v[68:69], s[100:101], v[194:195]
	v_pk_fma_f32 v[232:233], v[70:71], s[100:101], v[196:197]
	s_waitcnt lgkmcnt(1)
	v_pk_fma_f32 v[218:219], v[90:91], s[100:101], v[242:243]
	v_pk_fma_f32 v[220:221], v[92:93], s[100:101], v[244:245]
	v_pk_fma_f32 v[234:235], v[72:73], s[100:101], v[242:243]
	v_pk_fma_f32 v[236:237], v[74:75], s[100:101], v[244:245]
	s_waitcnt lgkmcnt(0)
	v_pk_fma_f32 v[222:223], v[94:95], s[100:101], v[246:247]
	v_pk_fma_f32 v[224:225], v[96:97], s[100:101], v[248:249]
	v_pk_fma_f32 v[238:239], v[76:77], s[100:101], v[246:247]
	v_pk_fma_f32 v[240:241], v[78:79], s[100:101], v[248:249]
	v_max3_f32 v84, v210, s31, v211
	v_max3_f32 v85, v226, s31, v227
	v_max3_f32 v84, v84, v212, v213
	v_max3_f32 v85, v85, v228, v229
	v_max3_f32 v84, v84, v214, v215
	v_max3_f32 v85, v85, v230, v231
	v_max3_f32 v84, v84, v216, v217
	v_max3_f32 v85, v85, v232, v233
	v_max3_f32 v84, v84, v218, v219
	v_max3_f32 v85, v85, v234, v235
	v_max3_f32 v84, v84, v220, v221
	v_max3_f32 v85, v85, v236, v237
	v_max3_f32 v84, v84, v222, v223
	v_max3_f32 v85, v85, v238, v239
	v_max3_f32 v84, v84, v224, v225
	v_max3_f32 v85, v85, v240, v241
	ds_bpermute_b32 v86, v250, v84
	ds_bpermute_b32 v87, v250, v85
	s_waitcnt lgkmcnt(0)
	v_max_f32_e32 v84, v84, v86
	v_max_f32_e32 v85, v85, v87
	v_lshlrev_b32_e32 v250, 2, v185
	ds_bpermute_b32 v86, v250, v84
	ds_bpermute_b32 v87, v250, v85
	s_waitcnt lgkmcnt(0)
	v_max3_f32 v131, v114, v84, v86
	v_max3_f32 v173, v112, v85, v87
	v_sub_f32_e32 v84, v114, v131
	v_sub_f32_e32 v85, v112, v173
	v_exp_f32_e32 v126, v84
	v_exp_f32_e32 v82, v85
	v_sub_f32_e32 v86, 0, v131
	v_sub_f32_e32 v80, 0, v173
	v_pk_add_f32 v[210:211], v[210:211], v[86:87] op_sel_hi:[1,0]
	v_pk_add_f32 v[212:213], v[212:213], v[86:87] op_sel_hi:[1,0]
	v_pk_add_f32 v[226:227], v[226:227], v[80:81] op_sel_hi:[1,0]
	v_pk_add_f32 v[228:229], v[228:229], v[80:81] op_sel_hi:[1,0]
	v_pk_add_f32 v[214:215], v[214:215], v[86:87] op_sel_hi:[1,0]
	v_pk_add_f32 v[216:217], v[216:217], v[86:87] op_sel_hi:[1,0]
	v_pk_add_f32 v[230:231], v[230:231], v[80:81] op_sel_hi:[1,0]
	v_pk_add_f32 v[232:233], v[232:233], v[80:81] op_sel_hi:[1,0]
	v_pk_add_f32 v[218:219], v[218:219], v[86:87] op_sel_hi:[1,0]
	v_pk_add_f32 v[220:221], v[220:221], v[86:87] op_sel_hi:[1,0]
	v_pk_add_f32 v[234:235], v[234:235], v[80:81] op_sel_hi:[1,0]
	v_pk_add_f32 v[236:237], v[236:237], v[80:81] op_sel_hi:[1,0]
	v_pk_add_f32 v[222:223], v[222:223], v[86:87] op_sel_hi:[1,0]
	v_pk_add_f32 v[224:225], v[224:225], v[86:87] op_sel_hi:[1,0]
	v_pk_add_f32 v[238:239], v[238:239], v[80:81] op_sel_hi:[1,0]
	v_pk_add_f32 v[240:241], v[240:241], v[80:81] op_sel_hi:[1,0]
	v_exp_f32_e32 v155, v210
	v_exp_f32_e32 v154, v226
	v_exp_f32_e32 v157, v211
	v_exp_f32_e32 v156, v227
	v_exp_f32_e32 v151, v212
	v_exp_f32_e32 v150, v228
	v_exp_f32_e32 v153, v213
	v_exp_f32_e32 v152, v229
	v_exp_f32_e32 v117, v214
	v_exp_f32_e32 v116, v230
	v_exp_f32_e32 v119, v215
	v_exp_f32_e32 v118, v231
	v_exp_f32_e32 v123, v216
	v_exp_f32_e32 v122, v232
	v_exp_f32_e32 v121, v217
	v_exp_f32_e32 v120, v233
	v_exp_f32_e32 v125, v218
	v_exp_f32_e32 v124, v234
	v_exp_f32_e32 v89, v219
	v_exp_f32_e32 v88, v235
	v_exp_f32_e32 v95, v220
	v_exp_f32_e32 v94, v236
	v_exp_f32_e32 v115, v221
	v_exp_f32_e32 v114, v237
	v_exp_f32_e32 v93, v222
	v_exp_f32_e32 v92, v238
	v_exp_f32_e32 v113, v223
	v_exp_f32_e32 v112, v239
	v_exp_f32_e32 v91, v224
	v_exp_f32_e32 v90, v240
	v_exp_f32_e32 v97, v225
	v_exp_f32_e32 v96, v241
	v_add_u32_e32 v242, 0x4800, v170
	v_add_u32_e32 v243, 0x5000, v170
	v_add_u32_e32 v244, 0x5800, v170
	v_add_u32_e32 v245, 0x6000, v170
	ds_read2_b64 v[210:213], v242 offset1:4
	ds_read2_b64 v[214:217], v243 offset0:32 offset1:36
	ds_read2_b64 v[218:221], v244 offset0:64 offset1:68
	ds_read2_b64 v[222:225], v245 offset0:96 offset1:100
	ds_read2_b64 v[226:229], v242 offset0:8 offset1:12
	ds_read2_b64 v[230:233], v243 offset0:40 offset1:44
	ds_read2_b64 v[234:237], v244 offset0:72 offset1:76
	ds_read2_b64 v[238:241], v245 offset0:104 offset1:108
	v_pk_mul_f32 v[202:203], v[52:53], v[126:127] op_sel_hi:[1,0]
	v_pk_mul_f32 v[52:53], v[56:57], v[126:127] op_sel_hi:[1,0]
	v_pk_mul_f32 v[198:199], v[48:49], v[126:127] op_sel_hi:[1,0]
	v_pk_mul_f32 v[48:49], v[60:61], v[126:127] op_sel_hi:[1,0]
	v_pk_mul_f32 v[200:201], v[50:51], v[126:127] op_sel_hi:[1,0]
	v_pk_mul_f32 v[204:205], v[54:55], v[126:127] op_sel_hi:[1,0]
	v_pk_add_f32 v[64:65], v[154:155], 0 op_sel_hi:[1,0]
	v_pk_add_f32 v[80:81], v[156:157], v[64:65]
	v_pk_mul_f32 v[46:47], v[46:47], v[82:83] op_sel_hi:[1,0]
	v_pk_mul_f32 v[44:45], v[44:45], v[82:83] op_sel_hi:[1,0]
	v_pk_mul_f32 v[54:55], v[58:59], v[126:127] op_sel_hi:[1,0]
	v_cvt_pk_bf16_f32 v56, v155, v157
	v_cvt_pk_bf16_f32 v57, v151, v153
	v_cvt_pk_bf16_f32 v58, v117, v119
	v_cvt_pk_bf16_f32 v59, v123, v121
	v_cvt_pk_bf16_f32 v68, v154, v156
	s_waitcnt lgkmcnt(7)
; DEVI unsigned pk_bf16(float lo, float hi) { unsigned r; asm("v_cvt_pk_bf16_f32 %0, %1, %2" : "=v"(r) : "v"(lo), "v"(hi)); return r; }
; DEVI bf16x8 mk8(uint2 a, uint2 b) { union { uint4 u; bf16x8 v; } c; c.u = make_uint4(a.x, a.y, b.x, b.y); return c.v; }
; #define MFMA(a, b, c) __builtin_amdgcn_mfma_f32_16x16x32_bf16((a), (b), (c), 0, 0, 0)
; template <int DK, bool BIAS> ...
;     ...
;         float ps = 0.f;
; #pragma unroll
;         for (int kt = 0; kt < 4; ++kt)
; #pragma unroll
;           for (int r = 0; r < 4; ++r) { const float pv = BIAS ? __builtin_amdgcn_exp2f(S[kt][qi][r] - mnew) : __builtin_amdgcn_exp2f(fmaf(S[kt][qi][r], sc2, -mnew)); S[kt][qi][r] = pv; ps += pv; }
;         {
;           const float alpha = __builtin_amdgcn_exp2f(mold - mnew);
;           lrun[qi] *= alpha;
; #pragma unroll
;           for (int et = 0; et < 4; ++et) O[et][qi] *= alpha;
;         }
;         lrun[qi] += ps;
; #pragma unroll
;         for (int k2 = 0; k2 < 2; ++k2) { uint2 lo, hi; lo.x = pk_bf16(S[2 * k2][qi][0], S[2 * k2][qi][1]); lo.y = pk_bf16(S[2 * k2][qi][2], S[2 * k2][qi][3]);
;           hi.x = pk_bf16(S[2 * k2 + 1][qi][0], S[2 * k2 + 1][qi][1]); hi.y = pk_bf16(S[2 * k2 + 1][qi][2], S[2 * k2 + 1][qi][3]); pf[qi][k2] = mk8(lo, hi); }
;       }
; #pragma unroll
;       for (int k2 = 0; k2 < 2; ++k2)
; #pragma unroll
;         for (int et = 0; et < 4; ++et) {
;           const uint2 v0 = *(const uint2*)(Vtm + (buf * 64 + 16 * et + fr) * 72 + 32 * k2 + 4 * fq), v1 = *(const uint2*)(Vtm + (buf * 64 + 16 * et + fr) * 72 + 32 * k2 + 16 + 4 * fq);
;           const bf16x8 va = mk8(v0, v1);
; #pragma unroll
;           for (int qi = 0; qi < 2; ++qi) O[et][qi] = MFMA(va, pf[qi][k2], O[et][qi]);
;         }
	v_mfma_f32_16x16x32_bf16 v[76:79], v[210:213], v[56:59], v[198:201]
	v_cvt_pk_bf16_f32 v69, v150, v152
	v_cvt_pk_bf16_f32 v70, v116, v118
	v_cvt_pk_bf16_f32 v71, v122, v120
	v_pk_mul_f32 v[42:43], v[42:43], v[82:83] op_sel_hi:[1,0]
	s_nop 0
	v_mfma_f32_16x16x32_bf16 v[44:47], v[210:213], v[68:71], v[44:47]
	v_pk_mul_f32 v[40:41], v[40:41], v[82:83] op_sel_hi:[1,0]
	s_waitcnt lgkmcnt(6)
	v_mfma_f32_16x16x32_bf16 v[84:87], v[214:217], v[56:59], v[202:205]
	v_pk_mul_f32 v[50:51], v[62:63], v[126:127] op_sel_hi:[1,0]
	v_mfma_f32_16x16x32_bf16 v[40:43], v[214:217], v[68:71], v[40:43]
	v_pk_mul_f32 v[38:39], v[38:39], v[82:83] op_sel_hi:[1,0]
	v_pk_mul_f32 v[36:37], v[36:37], v[82:83] op_sel_hi:[1,0]
	s_waitcnt lgkmcnt(5)
	v_mfma_f32_16x16x32_bf16 v[154:157], v[218:221], v[56:59], v[52:55]
	v_pk_mul_f32 v[34:35], v[34:35], v[82:83] op_sel_hi:[1,0]
	v_pk_mul_f32 v[32:33], v[32:33], v[82:83] op_sel_hi:[1,0]
	v_cvt_pk_bf16_f32 v60, v125, v89
	v_mfma_f32_16x16x32_bf16 v[36:39], v[218:221], v[68:71], v[36:39]
	s_waitcnt lgkmcnt(4)
	v_mfma_f32_16x16x32_bf16 v[64:67], v[222:225], v[56:59], v[48:51]
	v_cvt_pk_bf16_f32 v61, v95, v115
	v_cvt_pk_bf16_f32 v62, v93, v113
	v_cvt_pk_bf16_f32 v63, v91, v97
	s_nop 0
	v_mfma_f32_16x16x32_bf16 v[32:35], v[222:225], v[68:71], v[32:35]
	v_cvt_pk_bf16_f32 v68, v124, v88
	v_cvt_pk_bf16_f32 v69, v94, v114
	s_waitcnt lgkmcnt(3)
	v_mfma_f32_16x16x32_bf16 v[48:51], v[226:229], v[60:63], v[76:79]
	v_cvt_pk_bf16_f32 v70, v92, v112
	v_cvt_pk_bf16_f32 v71, v90, v96
	s_nop 1
	v_mfma_f32_16x16x32_bf16 v[44:47], v[226:229], v[68:71], v[44:47]
	v_pk_add_f32 v[52:53], v[150:151], v[80:81]
	v_mov_b32_e32 v83, v126
	v_pk_add_f32 v[76:77], v[152:153], v[52:53]
	s_waitcnt lgkmcnt(2)
	v_mfma_f32_16x16x32_bf16 v[52:55], v[230:233], v[60:63], v[84:87]
	v_pk_add_f32 v[76:77], v[116:117], v[76:77]
	v_pk_add_f32 v[76:77], v[118:119], v[76:77]
	v_mfma_f32_16x16x32_bf16 v[40:43], v[230:233], v[68:71], v[40:43]
	v_pk_add_f32 v[76:77], v[122:123], v[76:77]
	v_pk_add_f32 v[56:57], v[120:121], v[76:77]
	v_pk_add_f32 v[80:81], v[124:125], v[56:57]
	s_waitcnt lgkmcnt(1)
	v_mfma_f32_16x16x32_bf16 v[56:59], v[234:237], v[60:63], v[154:157]
	v_pk_add_f32 v[80:81], v[88:89], v[80:81]
	v_pk_add_f32 v[80:81], v[94:95], v[80:81]
	v_mfma_f32_16x16x32_bf16 v[36:39], v[234:237], v[68:71], v[36:39]
	v_pk_add_f32 v[80:81], v[114:115], v[80:81]
	v_mov_b32_e32 v114, v131
	v_pk_add_f32 v[72:73], v[92:93], v[80:81]
	s_waitcnt lgkmcnt(0)
	v_mfma_f32_16x16x32_bf16 v[60:63], v[238:241], v[60:63], v[64:67]
	v_pk_add_f32 v[72:73], v[112:113], v[72:73]
	v_mov_b32_e32 v112, v173
	v_mfma_f32_16x16x32_bf16 v[32:35], v[238:241], v[68:71], v[32:35]
	v_pk_add_f32 v[64:65], v[90:91], v[72:73]
	v_pk_add_f32 v[64:65], v[96:97], v[64:65]
	s_nop 0
	v_pk_fma_f32 v[106:107], v[106:107], v[82:83], v[64:65]

; #define MFMA(a, b, c) __builtin_amdgcn_mfma_f32_16x16x32_bf16((a), (b), (c), 0, 0, 0)
; template <int DK, bool BIAS> ...
;     ...
; #pragma unroll
;       for (int ks = 0; ks < KS; ++ks)
; #pragma unroll
;         for (int kt = 0; kt < 4; ++kt) { const bf16x8 ak = *(const bf16x8*)(Ksm + (buf * 64 + 16 * kt + fr) * KST + 32 * ks + 8 * fq);
; #pragma unroll
;           for (int qi = 0; qi < 2; ++qi) S[kt][qi] = MFMA(ak, qf[qi][ks], S[kt][qi]); }
;       bf16x8 pf[2][2];
;       if (64 * j + 63 > q0 + 32 * w) {
; #pragma unroll
;         for (int qi = 0; qi < 2; ++qi) { const int qg = q0 + 32 * w + 16 * qi + fr;
; #pragma unroll
;           for (int kt = 0; kt < 4; ++kt)
; #pragma unroll
;             for (int r = 0; r < 4; ++r) { const int kg = 64 * j + 16 * kt + 4 * fq + r; if (kg > qg) S[kt][qi][r] = -1e30f; } }
;       }
; #pragma unroll
;       for (int qi = 0; qi < 2; ++qi) {
;         float mx = -3e38f;
;         if (BIAS) {
; #pragma unroll
;           for (int kt = 0; kt < 4; ++kt) { const f32x4 nf = *(const f32x4*)(fkm + buf * 64 + 16 * kt + 4 * fq);
; #pragma unroll
;             for (int r = 0; r < 4; ++r) { const float t = fmaf(S[kt][qi][r], sc2, nf[r]); S[kt][qi][r] = t; mx = fmaxf(mx, t); } }
.LBB0_1793:
	s_and_saveexec_b64 s[0:1], s[8:9]
	s_cbranch_execz .LBB0_1799
	s_add_i32 s18, s38, 64
	v_cmp_le_i32_e32 vcc, s18, v167
	s_and_saveexec_b64 s[92:93], vcc
	s_cbranch_execz .LBB0_1798
	ds_read_b128 v[80:83], v169 offset:13824
	ds_read_b128 v[64:67], v169 offset:9216
	ds_read_b128 v[84:87], v169 offset:9280
	ds_read_b128 v[72:75], v169 offset:11520
	ds_read_b128 v[210:213], v169 offset:16128
	ds_read_b128 v[214:217], v169 offset:11584
	ds_read_b128 v[218:221], v169 offset:16192
	ds_read_b128 v[222:225], v169 offset:13888
	ds_read_b128 v[174:177], v104 offset:37120
	ds_read_b128 v[194:197], v104 offset:37184
	ds_read_b128 v[242:245], v104 offset:37248
	ds_read_b128 v[246:249], v104 offset:37312
	s_add_i32 s18, s38, 0x7f
	v_cmp_gt_i32_e32 vcc, s18, v127
	s_waitcnt lgkmcnt(11)
	v_mfma_f32_16x16x32_bf16 v[90:93], v[80:83], v[4:7], 0
	v_mfma_f32_16x16x32_bf16 v[94:97], v[80:83], v[12:15], 0
	s_waitcnt lgkmcnt(10)
	v_mfma_f32_16x16x32_bf16 v[68:71], v[64:67], v[4:7], 0
	s_waitcnt lgkmcnt(7)
	v_mfma_f32_16x16x32_bf16 v[116:119], v[210:213], v[4:7], 0
	v_mfma_f32_16x16x32_bf16 v[120:123], v[210:213], v[12:15], 0
	v_mfma_f32_16x16x32_bf16 v[80:83], v[84:87], v[0:3], v[68:71]
	v_mfma_f32_16x16x32_bf16 v[64:67], v[64:67], v[12:15], 0
	v_mfma_f32_16x16x32_bf16 v[76:79], v[72:75], v[4:7], 0
	v_mfma_f32_16x16x32_bf16 v[72:75], v[72:75], v[12:15], 0
	v_mfma_f32_16x16x32_bf16 v[64:67], v[84:87], v[8:11], v[64:67]
	s_waitcnt lgkmcnt(6)
	v_mfma_f32_16x16x32_bf16 v[86:89], v[214:217], v[0:3], v[76:79]
	v_mfma_f32_16x16x32_bf16 v[68:71], v[214:217], v[8:11], v[72:75]
	s_waitcnt lgkmcnt(4)
	v_mfma_f32_16x16x32_bf16 v[90:93], v[222:225], v[0:3], v[90:93]
	v_mfma_f32_16x16x32_bf16 v[72:75], v[222:225], v[8:11], v[94:97]
	v_mfma_f32_16x16x32_bf16 v[94:97], v[218:221], v[0:3], v[116:119]
	v_mfma_f32_16x16x32_bf16 v[76:79], v[218:221], v[8:11], v[120:123]
	s_and_saveexec_b64 s[18:19], vcc
	s_cbranch_execz .LBB0_1797
	v_add_u32_e32 v85, s38, v103
	v_add_u32_e32 v113, 64, v85
	v_mov_b32_e32 v84, s30
	v_cmp_gt_i32_e32 vcc, v113, v158
	v_add_u32_e32 v115, 0x42, v85
	v_add_u32_e32 v116, 0x43, v85
	v_cndmask_b32_e32 v84, v80, v84, vcc
	v_cmp_lt_i32_e32 vcc, v113, v158
	v_add_u32_e32 v117, 0x50, v85
	v_add_u32_e32 v118, 0x51, v85
	v_cndmask_b32_e32 v80, v84, v80, vcc
	v_cndmask_b32_e32 v81, v193, v81, vcc
	v_cmp_le_i32_e32 vcc, v115, v158
	v_mov_b32_e32 v84, s30
	v_add_u32_e32 v119, 0x52, v85
	v_cndmask_b32_e32 v82, v193, v82, vcc
	v_cmp_le_i32_e32 vcc, v116, v158
	v_add_u32_e32 v120, 0x53, v85
	v_add_u32_e32 v121, 0x60, v85
	v_cndmask_b32_e32 v83, v193, v83, vcc
	v_cmp_gt_i32_e32 vcc, v117, v158
	v_add_u32_e32 v122, 0x61, v85
	v_add_u32_e32 v123, 0x62, v85
	v_cndmask_b32_e32 v86, v86, v84, vcc
	v_cmp_le_i32_e32 vcc, v118, v158
	v_add_u32_e32 v124, 0x63, v85
	v_add_u32_e32 v125, 0x70, v85
	v_cndmask_b32_e32 v87, v193, v87, vcc
	v_cmp_le_i32_e32 vcc, v119, v158
	v_add_u32_e32 v126, 0x71, v85
	v_add_u32_e32 v131, 0x72, v85
	v_cndmask_b32_e32 v88, v193, v88, vcc
	v_cmp_le_i32_e32 vcc, v120, v158
	v_add_u32_e32 v85, 0x73, v85
	s_nop 0
	v_cndmask_b32_e32 v89, v193, v89, vcc
	v_cmp_gt_i32_e32 vcc, v121, v158
	v_cmp_le_i32_e64 s[100:101], v122, v158
	s_nop 0
	v_cndmask_b32_e32 v90, v90, v84, vcc
	v_cndmask_b32_e64 v91, v193, v91, s[100:101]
	v_cmp_le_i32_e32 vcc, v123, v158
	v_cmp_le_i32_e64 s[100:101], v124, v158
	s_nop 0
	v_cndmask_b32_e32 v92, v193, v92, vcc
	v_cndmask_b32_e64 v93, v193, v93, s[100:101]
	v_cmp_gt_i32_e32 vcc, v125, v158
	v_cmp_le_i32_e64 s[100:101], v126, v158
	s_nop 0
	v_cndmask_b32_e32 v94, v94, v84, vcc
	v_cndmask_b32_e64 v95, v193, v95, s[100:101]
	v_cmp_le_i32_e32 vcc, v131, v158
	v_cmp_le_i32_e64 s[100:101], v85, v158
	s_nop 0
	v_cndmask_b32_e32 v96, v193, v96, vcc
	v_cndmask_b32_e64 v97, v193, v97, s[100:101]
	v_cmp_gt_i32_e32 vcc, v113, v105
	s_nop 1
	v_cndmask_b32_e32 v84, v64, v84, vcc
	v_cmp_lt_i32_e32 vcc, v113, v105
	s_nop 1
	v_cndmask_b32_e32 v64, v84, v64, vcc
	v_cndmask_b32_e32 v65, v193, v65, vcc
	v_cmp_le_i32_e32 vcc, v115, v105
	v_mov_b32_e32 v84, s30
	s_nop 0
	v_cndmask_b32_e32 v66, v193, v66, vcc
	v_cmp_le_i32_e32 vcc, v116, v105
	v_cmp_gt_i32_e64 s[100:101], v117, v105
	s_nop 0
	v_cndmask_b32_e32 v67, v193, v67, vcc
	v_cndmask_b32_e64 v68, v68, v84, s[100:101]
	v_cmp_le_i32_e32 vcc, v118, v105
	v_cmp_le_i32_e64 s[100:101], v119, v105
	s_nop 0
	v_cndmask_b32_e32 v69, v193, v69, vcc
	v_cndmask_b32_e64 v70, v193, v70, s[100:101]
	v_cmp_le_i32_e32 vcc, v120, v105
	v_cmp_gt_i32_e64 s[100:101], v121, v105
	s_nop 0
	v_cndmask_b32_e32 v71, v193, v71, vcc
	v_cndmask_b32_e64 v72, v72, v84, s[100:101]
	v_cmp_le_i32_e32 vcc, v122, v105
	v_cmp_le_i32_e64 s[100:101], v123, v105
	s_nop 0
	v_cndmask_b32_e32 v73, v193, v73, vcc
	v_cndmask_b32_e64 v74, v193, v74, s[100:101]
	v_cmp_le_i32_e32 vcc, v124, v105
	v_cmp_gt_i32_e64 s[100:101], v125, v105
	s_nop 0
	v_cndmask_b32_e32 v75, v193, v75, vcc
	v_cndmask_b32_e64 v76, v76, v84, s[100:101]
	v_cmp_le_i32_e32 vcc, v126, v105
	v_cmp_le_i32_e64 s[100:101], v131, v105
	s_nop 0
	v_cndmask_b32_e32 v77, v193, v77, vcc
	v_cndmask_b32_e64 v78, v193, v78, s[100:101]
	v_cmp_le_i32_e32 vcc, v85, v105
	s_nop 1
	v_cndmask_b32_e32 v79, v193, v79, vcc
; DEVI unsigned pk_bf16(float lo, float hi) { unsigned r; asm("v_cvt_pk_bf16_f32 %0, %1, %2" : "=v"(r) : "v"(lo), "v"(hi)); return r; }
; DEVI bf16x8 mk8(uint2 a, uint2 b) { union { uint4 u; bf16x8 v; } c; c.u = make_uint4(a.x, a.y, b.x, b.y); return c.v; }
; template <int DK, bool BIAS> ...
;     ...
; #pragma unroll
;       for (int qi = 0; qi < 2; ++qi) {
;         float mx = -3e38f;
;         if (BIAS) {
; #pragma unroll
;           for (int kt = 0; kt < 4; ++kt) { const f32x4 nf = *(const f32x4*)(fkm + buf * 64 + 16 * kt + 4 * fq);
; #pragma unroll
;             for (int r = 0; r < 4; ++r) { const float t = fmaf(S[kt][qi][r], sc2, nf[r]); S[kt][qi][r] = t; mx = fmaxf(mx, t); } }
;         } else {
; #pragma unroll
;           for (int kt = 0; kt < 4; ++kt)
; #pragma unroll
;             for (int r = 0; r < 4; ++r) mx = fmaxf(mx, S[kt][qi][r]);
;           mx *= sc2;
;         }
;         mx = fmaxf(mx, __shfl_xor(mx, 16)); mx = fmaxf(mx, __shfl_xor(mx, 32));
;         const float mold = mrun[qi], mnew = fmaxf(mold, mx);
;         mrun[qi] = mnew;
;         float ps = 0.f;
; #pragma unroll
;         for (int kt = 0; kt < 4; ++kt)
; #pragma unroll
;           for (int r = 0; r < 4; ++r) { const float pv = BIAS ? __builtin_amdgcn_exp2f(S[kt][qi][r] - mnew) : __builtin_amdgcn_exp2f(fmaf(S[kt][qi][r], sc2, -mnew)); S[kt][qi][r] = pv; ps += pv; }
;         {
;           const float alpha = __builtin_amdgcn_exp2f(mold - mnew);
;           lrun[qi] *= alpha;
; #pragma unroll
;           for (int et = 0; et < 4; ++et) O[et][qi] *= alpha;
;         }
;         lrun[qi] += ps;
; #pragma unroll
;         for (int k2 = 0; k2 < 2; ++k2) { uint2 lo, hi; lo.x = pk_bf16(S[2 * k2][qi][0], S[2 * k2][qi][1]); lo.y = pk_bf16(S[2 * k2][qi][2], S[2 * k2][qi][3]);
;           hi.x = pk_bf16(S[2 * k2 + 1][qi][0], S[2 * k2 + 1][qi][1]); hi.y = pk_bf16(S[2 * k2 + 1][qi][2], S[2 * k2 + 1][qi][3]); pf[qi][k2] = mk8(lo, hi); }
;       }
; #pragma unroll
;       for (int k2 = 0; k2 < 2; ++k2)
; #pragma unroll
;         for (int et = 0; et < 4; ++et) {
;           const uint2 v0 = *(const uint2*)(Vtm + (buf * 64 + 16 * et + fr) * 72 + 32 * k2 + 4 * fq), v1 = *(const uint2*)(Vtm + (buf * 64 + 16 * et + fr) * 72 + 32 * k2 + 16 + 4 * fq);
;           const bf16x8 va = mk8(v0, v1);
.LBB0_1797:
	s_or_b64 exec, exec, s[18:19]
	s_mov_b32 s100, 0x3e38aa3b
	s_mov_b32 s101, 0x3e38aa3b
	v_lshlrev_b32_e32 v250, 2, v186
	s_waitcnt lgkmcnt(3)
	v_pk_fma_f32 v[210:211], v[80:81], s[100:101], v[174:175]
	v_pk_fma_f32 v[212:213], v[82:83], s[100:101], v[176:177]
	v_pk_fma_f32 v[226:227], v[64:65], s[100:101], v[174:175]
	v_pk_fma_f32 v[228:229], v[66:67], s[100:101], v[176:177]
	s_waitcnt lgkmcnt(2)
	v_pk_fma_f32 v[214:215], v[86:87], s[100:101], v[194:195]
	v_pk_fma_f32 v[216:217], v[88:89], s[100:101], v[196:197]
	v_pk_fma_f32 v[230:231], v[68:69], s[100:101], v[194:195]
	v_pk_fma_f32 v[232:233], v[70:71], s[100:101], v[196:197]
	s_waitcnt lgkmcnt(1)
	v_pk_fma_f32 v[218:219], v[90:91], s[100:101], v[242:243]
	v_pk_fma_f32 v[220:221], v[92:93], s[100:101], v[244:245]
	v_pk_fma_f32 v[234:235], v[72:73], s[100:101], v[242:243]
	v_pk_fma_f32 v[236:237], v[74:75], s[100:101], v[244:245]
	s_waitcnt lgkmcnt(0)
	v_pk_fma_f32 v[222:223], v[94:95], s[100:101], v[246:247]
	v_pk_fma_f32 v[224:225], v[96:97], s[100:101], v[248:249]
	v_pk_fma_f32 v[238:239], v[76:77], s[100:101], v[246:247]
	v_pk_fma_f32 v[240:241], v[78:79], s[100:101], v[248:249]
	v_max3_f32 v84, v210, s31, v211
	v_max3_f32 v85, v226, s31, v227
	v_max3_f32 v84, v84, v212, v213
	v_max3_f32 v85, v85, v228, v229
	v_max3_f32 v84, v84, v214, v215
	v_max3_f32 v85, v85, v230, v231
	v_max3_f32 v84, v84, v216, v217
	v_max3_f32 v85, v85, v232, v233
	v_max3_f32 v84, v84, v218, v219
	v_max3_f32 v85, v85, v234, v235
	v_max3_f32 v84, v84, v220, v221
	v_max3_f32 v85, v85, v236, v237
	v_max3_f32 v84, v84, v222, v223
	v_max3_f32 v85, v85, v238, v239
	v_max3_f32 v84, v84, v224, v225
	v_max3_f32 v85, v85, v240, v241
	ds_bpermute_b32 v86, v250, v84
	ds_bpermute_b32 v87, v250, v85
	s_waitcnt lgkmcnt(0)
	v_max_f32_e32 v84, v84, v86
	v_max_f32_e32 v85, v85, v87
	v_lshlrev_b32_e32 v250, 2, v185
	ds_bpermute_b32 v86, v250, v84
	ds_bpermute_b32 v87, v250, v85
	s_waitcnt lgkmcnt(0)
	v_max3_f32 v131, v114, v84, v86
	v_max3_f32 v173, v112, v85, v87
	v_sub_f32_e32 v84, v114, v131
	v_sub_f32_e32 v85, v112, v173
	v_exp_f32_e32 v126, v84
	v_exp_f32_e32 v82, v85
	v_sub_f32_e32 v86, 0, v131
	v_sub_f32_e32 v80, 0, v173
	v_pk_add_f32 v[210:211], v[210:211], v[86:87] op_sel_hi:[1,0]
	v_pk_add_f32 v[212:213], v[212:213], v[86:87] op_sel_hi:[1,0]
	v_pk_add_f32 v[226:227], v[226:227], v[80:81] op_sel_hi:[1,0]
	v_pk_add_f32 v[228:229], v[228:229], v[80:81] op_sel_hi:[1,0]
	v_pk_add_f32 v[214:215], v[214:215], v[86:87] op_sel_hi:[1,0]
	v_pk_add_f32 v[216:217], v[216:217], v[86:87] op_sel_hi:[1,0]
	v_pk_add_f32 v[230:231], v[230:231], v[80:81] op_sel_hi:[1,0]
	v_pk_add_f32 v[232:233], v[232:233], v[80:81] op_sel_hi:[1,0]
	v_pk_add_f32 v[218:219], v[218:219], v[86:87] op_sel_hi:[1,0]
	v_pk_add_f32 v[220:221], v[220:221], v[86:87] op_sel_hi:[1,0]
	v_pk_add_f32 v[234:235], v[234:235], v[80:81] op_sel_hi:[1,0]
	v_pk_add_f32 v[236:237], v[236:237], v[80:81] op_sel_hi:[1,0]
	v_pk_add_f32 v[222:223], v[222:223], v[86:87] op_sel_hi:[1,0]
	v_pk_add_f32 v[224:225], v[224:225], v[86:87] op_sel_hi:[1,0]
	v_pk_add_f32 v[238:239], v[238:239], v[80:81] op_sel_hi:[1,0]
	v_pk_add_f32 v[240:241], v[240:241], v[80:81] op_sel_hi:[1,0]
	v_exp_f32_e32 v155, v210
	v_exp_f32_e32 v154, v226
	v_exp_f32_e32 v157, v211
	v_exp_f32_e32 v156, v227
	v_exp_f32_e32 v151, v212
	v_exp_f32_e32 v150, v228
	v_exp_f32_e32 v153, v213
	v_exp_f32_e32 v152, v229
	v_exp_f32_e32 v117, v214
	v_exp_f32_e32 v116, v230
	v_exp_f32_e32 v119, v215
	v_exp_f32_e32 v118, v231
	v_exp_f32_e32 v123, v216
	v_exp_f32_e32 v122, v232
	v_exp_f32_e32 v121, v217
	v_exp_f32_e32 v120, v233
	v_exp_f32_e32 v125, v218
	v_exp_f32_e32 v124, v234
	v_exp_f32_e32 v89, v219
	v_exp_f32_e32 v88, v235
	v_exp_f32_e32 v95, v220
	v_exp_f32_e32 v94, v236
	v_exp_f32_e32 v115, v221
	v_exp_f32_e32 v114, v237
	v_exp_f32_e32 v93, v222
	v_exp_f32_e32 v92, v238
	v_exp_f32_e32 v113, v223
	v_exp_f32_e32 v112, v239
	v_exp_f32_e32 v91, v224
	v_exp_f32_e32 v90, v240
	v_exp_f32_e32 v97, v225
	v_exp_f32_e32 v96, v241
	v_add_u32_e32 v242, 0x6800, v170
	v_add_u32_e32 v243, 0x7000, v170
	v_add_u32_e32 v244, 0x7800, v170
	v_add_u32_e32 v245, 0x8000, v170
	ds_read2_b64 v[210:213], v242 offset0:128 offset1:132
	ds_read2_b64 v[214:217], v243 offset0:160 offset1:164
	ds_read2_b64 v[218:221], v244 offset0:192 offset1:196
	ds_read2_b64 v[222:225], v245 offset0:224 offset1:228
	ds_read2_b64 v[226:229], v242 offset0:136 offset1:140
	ds_read2_b64 v[230:233], v243 offset0:168 offset1:172
	ds_read2_b64 v[234:237], v244 offset0:200 offset1:204
	ds_read2_b64 v[238:241], v245 offset0:232 offset1:236
	v_pk_mul_f32 v[202:203], v[52:53], v[126:127] op_sel_hi:[1,0]
	v_pk_mul_f32 v[52:53], v[56:57], v[126:127] op_sel_hi:[1,0]
	v_pk_mul_f32 v[198:199], v[48:49], v[126:127] op_sel_hi:[1,0]
	v_pk_mul_f32 v[48:49], v[60:61], v[126:127] op_sel_hi:[1,0]
	v_pk_mul_f32 v[200:201], v[50:51], v[126:127] op_sel_hi:[1,0]
	v_pk_mul_f32 v[204:205], v[54:55], v[126:127] op_sel_hi:[1,0]
	v_pk_add_f32 v[64:65], v[154:155], 0 op_sel_hi:[1,0]
	v_pk_add_f32 v[80:81], v[156:157], v[64:65]
	v_pk_mul_f32 v[46:47], v[46:47], v[82:83] op_sel_hi:[1,0]
	v_pk_mul_f32 v[44:45], v[44:45], v[82:83] op_sel_hi:[1,0]
	v_pk_mul_f32 v[54:55], v[58:59], v[126:127] op_sel_hi:[1,0]
	v_cvt_pk_bf16_f32 v56, v155, v157
	v_cvt_pk_bf16_f32 v57, v151, v153
	v_cvt_pk_bf16_f32 v58, v117, v119
	v_cvt_pk_bf16_f32 v59, v123, v121
	v_cvt_pk_bf16_f32 v68, v154, v156
	s_waitcnt lgkmcnt(7)
; DEVI unsigned pk_bf16(float lo, float hi) { unsigned r; asm("v_cvt_pk_bf16_f32 %0, %1, %2" : "=v"(r) : "v"(lo), "v"(hi)); return r; }
; DEVI bf16x8 mk8(uint2 a, uint2 b) { union { uint4 u; bf16x8 v; } c; c.u = make_uint4(a.x, a.y, b.x, b.y); return c.v; }
; #define MFMA(a, b, c) __builtin_amdgcn_mfma_f32_16x16x32_bf16((a), (b), (c), 0, 0, 0)
; template <int DK, bool BIAS> ...
;     ...
;         float ps = 0.f;
; #pragma unroll
;         for (int kt = 0; kt < 4; ++kt)
; #pragma unroll
;           for (int r = 0; r < 4; ++r) { const float pv = BIAS ? __builtin_amdgcn_exp2f(S[kt][qi][r] - mnew) : __builtin_amdgcn_exp2f(fmaf(S[kt][qi][r], sc2, -mnew)); S[kt][qi][r] = pv; ps += pv; }
;         {
;           const float alpha = __builtin_amdgcn_exp2f(mold - mnew);
;           lrun[qi] *= alpha;
; #pragma unroll
;           for (int et = 0; et < 4; ++et) O[et][qi] *= alpha;
;         }
;         lrun[qi] += ps;
; #pragma unroll
;         for (int k2 = 0; k2 < 2; ++k2) { uint2 lo, hi; lo.x = pk_bf16(S[2 * k2][qi][0], S[2 * k2][qi][1]); lo.y = pk_bf16(S[2 * k2][qi][2], S[2 * k2][qi][3]);
;           hi.x = pk_bf16(S[2 * k2 + 1][qi][0], S[2 * k2 + 1][qi][1]); hi.y = pk_bf16(S[2 * k2 + 1][qi][2], S[2 * k2 + 1][qi][3]); pf[qi][k2] = mk8(lo, hi); }
;       }
; #pragma unroll
;       for (int k2 = 0; k2 < 2; ++k2)
; #pragma unroll
;         for (int et = 0; et < 4; ++et) {
;           const uint2 v0 = *(const uint2*)(Vtm + (buf * 64 + 16 * et + fr) * 72 + 32 * k2 + 4 * fq), v1 = *(const uint2*)(Vtm + (buf * 64 + 16 * et + fr) * 72 + 32 * k2 + 16 + 4 * fq);
;           const bf16x8 va = mk8(v0, v1);
; #pragma unroll
;           for (int qi = 0; qi < 2; ++qi) O[et][qi] = MFMA(va, pf[qi][k2], O[et][qi]);
;         }
	v_mfma_f32_16x16x32_bf16 v[76:79], v[210:213], v[56:59], v[198:201]
	v_cvt_pk_bf16_f32 v69, v150, v152
	v_cvt_pk_bf16_f32 v70, v116, v118
	v_cvt_pk_bf16_f32 v71, v122, v120
	v_pk_mul_f32 v[42:43], v[42:43], v[82:83] op_sel_hi:[1,0]
	s_nop 0
	v_mfma_f32_16x16x32_bf16 v[44:47], v[210:213], v[68:71], v[44:47]
	v_pk_mul_f32 v[40:41], v[40:41], v[82:83] op_sel_hi:[1,0]
	s_waitcnt lgkmcnt(6)
	v_mfma_f32_16x16x32_bf16 v[84:87], v[214:217], v[56:59], v[202:205]
	v_pk_mul_f32 v[50:51], v[62:63], v[126:127] op_sel_hi:[1,0]
	v_mfma_f32_16x16x32_bf16 v[40:43], v[214:217], v[68:71], v[40:43]
	v_pk_mul_f32 v[38:39], v[38:39], v[82:83] op_sel_hi:[1,0]
	v_pk_mul_f32 v[36:37], v[36:37], v[82:83] op_sel_hi:[1,0]
	s_waitcnt lgkmcnt(5)
	v_mfma_f32_16x16x32_bf16 v[154:157], v[218:221], v[56:59], v[52:55]
	v_pk_mul_f32 v[34:35], v[34:35], v[82:83] op_sel_hi:[1,0]
	v_pk_mul_f32 v[32:33], v[32:33], v[82:83] op_sel_hi:[1,0]
	v_cvt_pk_bf16_f32 v60, v125, v89
	v_mfma_f32_16x16x32_bf16 v[36:39], v[218:221], v[68:71], v[36:39]
	s_waitcnt lgkmcnt(4)
	v_mfma_f32_16x16x32_bf16 v[64:67], v[222:225], v[56:59], v[48:51]
	v_cvt_pk_bf16_f32 v61, v95, v115
	v_cvt_pk_bf16_f32 v62, v93, v113
	v_cvt_pk_bf16_f32 v63, v91, v97
	s_nop 0
	v_mfma_f32_16x16x32_bf16 v[32:35], v[222:225], v[68:71], v[32:35]
	v_cvt_pk_bf16_f32 v68, v124, v88
	v_cvt_pk_bf16_f32 v69, v94, v114
	s_waitcnt lgkmcnt(3)
	v_mfma_f32_16x16x32_bf16 v[48:51], v[226:229], v[60:63], v[76:79]
	v_cvt_pk_bf16_f32 v70, v92, v112
	v_cvt_pk_bf16_f32 v71, v90, v96
	s_nop 1
	v_mfma_f32_16x16x32_bf16 v[44:47], v[226:229], v[68:71], v[44:47]
	v_pk_add_f32 v[52:53], v[150:151], v[80:81]
	v_mov_b32_e32 v83, v126
	v_pk_add_f32 v[76:77], v[152:153], v[52:53]
	s_waitcnt lgkmcnt(2)
	v_mfma_f32_16x16x32_bf16 v[52:55], v[230:233], v[60:63], v[84:87]
	v_pk_add_f32 v[76:77], v[116:117], v[76:77]
	v_pk_add_f32 v[76:77], v[118:119], v[76:77]
	v_mfma_f32_16x16x32_bf16 v[40:43], v[230:233], v[68:71], v[40:43]
	v_pk_add_f32 v[76:77], v[122:123], v[76:77]
	v_pk_add_f32 v[56:57], v[120:121], v[76:77]
	v_pk_add_f32 v[80:81], v[124:125], v[56:57]
	s_waitcnt lgkmcnt(1)
	v_mfma_f32_16x16x32_bf16 v[56:59], v[234:237], v[60:63], v[154:157]
	v_pk_add_f32 v[80:81], v[88:89], v[80:81]
	v_pk_add_f32 v[80:81], v[94:95], v[80:81]
	v_mfma_f32_16x16x32_bf16 v[36:39], v[234:237], v[68:71], v[36:39]
	v_pk_add_f32 v[80:81], v[114:115], v[80:81]
	v_mov_b32_e32 v114, v131
	v_pk_add_f32 v[72:73], v[92:93], v[80:81]
	s_waitcnt lgkmcnt(0)
	v_mfma_f32_16x16x32_bf16 v[60:63], v[238:241], v[60:63], v[64:67]
	v_pk_add_f32 v[72:73], v[112:113], v[72:73]
	v_mov_b32_e32 v112, v173
	v_mfma_f32_16x16x32_bf16 v[32:35], v[238:241], v[68:71], v[32:35]
	v_pk_add_f32 v[64:65], v[90:91], v[72:73]
	v_pk_add_f32 v[64:65], v[96:97], v[64:65]
	s_nop 0
	v_pk_fma_f32 v[106:107], v[106:107], v[82:83], v[64:65]
